# k-inner MFMA order also in the in-proj i8 K-loop (each accumulator's two k-steps back-to-back)
# baseline (speedup 1.0000x reference)
.LBB0_129:
	ds_read_b128 v[132:135], v155
	ds_read_b128 v[136:139], v155 offset:1024
	ds_read_b128 v[140:143], v155 offset:2048
	ds_read_b128 v[160:163], v155 offset:3072
	ds_read_b128 v[164:167], v156
	ds_read_b128 v[168:171], v156 offset:1024
	ds_read_b128 v[172:175], v156 offset:2048
	ds_read_b128 v[176:179], v156 offset:3072
	s_cmp_eq_u32 s82, 28
	s_cselect_b32 s36, s27, s78
	s_cselect_b32 s37, s21, s79
	s_cselect_b32 s34, s77, s80
	s_cselect_b32 s35, s19, s81
	s_add_u32 s30, s36, 0x8000
	s_addc_u32 s31, s37, 0
	ds_read_b128 v[180:183], v157
	ds_read_b128 v[184:187], v157 offset:1024
	ds_read_b128 v[188:191], v157 offset:2048
	ds_read_b128 v[192:195], v157 offset:3072
	ds_read_b128 v[196:199], v157 offset:4096
	ds_read_b128 v[200:203], v157 offset:5120
	ds_read_b128 v[204:207], v157 offset:6144
	ds_read_b128 v[208:211], v157 offset:7168
	s_add_u32 s84, s78, 0xffffc000
	s_addc_u32 s85, s79, -1
	s_mov_b32 m0, s74
	s_nop 0
	global_load_lds_dwordx4 v151, s[84:85]
	s_nop 0
	s_mov_b32 m0, s75
	s_nop 0
	global_load_lds_dwordx4 v153, s[84:85]
	s_waitcnt vmcnt(8)
	s_waitcnt lgkmcnt(0)
	s_setprio 1
	s_barrier
	v_mfma_i32_16x16x64_i8 v[124:127], v[132:135], v[180:183], v[124:127]
	v_mfma_i32_16x16x64_i8 v[124:127], v[136:139], v[184:187], v[124:127]
	v_mfma_i32_16x16x64_i8 v[120:123], v[140:143], v[180:183], v[120:123]
	v_mfma_i32_16x16x64_i8 v[120:123], v[160:163], v[184:187], v[120:123]
	v_mfma_i32_16x16x64_i8 v[112:115], v[140:143], v[188:191], v[112:115]
	v_mfma_i32_16x16x64_i8 v[112:115], v[160:163], v[192:195], v[112:115]
	v_mfma_i32_16x16x64_i8 v[116:119], v[132:135], v[188:191], v[116:119]
	v_mfma_i32_16x16x64_i8 v[116:119], v[136:139], v[192:195], v[116:119]
	v_mfma_i32_16x16x64_i8 v[108:111], v[132:135], v[196:199], v[108:111]
	v_mfma_i32_16x16x64_i8 v[108:111], v[136:139], v[200:203], v[108:111]
	v_mfma_i32_16x16x64_i8 v[104:107], v[140:143], v[196:199], v[104:107]
	v_mfma_i32_16x16x64_i8 v[104:107], v[160:163], v[200:203], v[104:107]
	v_mfma_i32_16x16x64_i8 v[96:99], v[140:143], v[204:207], v[96:99]
	v_mfma_i32_16x16x64_i8 v[96:99], v[160:163], v[208:211], v[96:99]
	v_mfma_i32_16x16x64_i8 v[100:103], v[132:135], v[204:207], v[100:103]
	v_mfma_i32_16x16x64_i8 v[100:103], v[136:139], v[208:211], v[100:103]
	s_setprio 0
	s_setprio 1
	v_mfma_i32_16x16x64_i8 v[92:95], v[164:167], v[180:183], v[92:95]
	v_mfma_i32_16x16x64_i8 v[92:95], v[168:171], v[184:187], v[92:95]
	v_mfma_i32_16x16x64_i8 v[88:91], v[172:175], v[180:183], v[88:91]
	v_mfma_i32_16x16x64_i8 v[88:91], v[176:179], v[184:187], v[88:91]
	v_mfma_i32_16x16x64_i8 v[80:83], v[172:175], v[188:191], v[80:83]
	v_mfma_i32_16x16x64_i8 v[80:83], v[176:179], v[192:195], v[80:83]
	v_mfma_i32_16x16x64_i8 v[84:87], v[164:167], v[188:191], v[84:87]
	v_mfma_i32_16x16x64_i8 v[84:87], v[168:171], v[192:195], v[84:87]
	v_mfma_i32_16x16x64_i8 v[76:79], v[164:167], v[196:199], v[76:79]
	v_mfma_i32_16x16x64_i8 v[76:79], v[168:171], v[200:203], v[76:79]
	v_mfma_i32_16x16x64_i8 v[72:75], v[172:175], v[196:199], v[72:75]
	v_mfma_i32_16x16x64_i8 v[72:75], v[176:179], v[200:203], v[72:75]
	v_mfma_i32_16x16x64_i8 v[64:67], v[172:175], v[204:207], v[64:67]
	v_mfma_i32_16x16x64_i8 v[64:67], v[176:179], v[208:211], v[64:67]
	v_mfma_i32_16x16x64_i8 v[68:71], v[164:167], v[204:207], v[68:71]
	v_mfma_i32_16x16x64_i8 v[68:71], v[168:171], v[208:211], v[68:71]
	s_setprio 0
	s_barrier
	ds_read_b128 v[180:183], v157 offset:16384
	ds_read_b128 v[184:187], v157 offset:17408
	ds_read_b128 v[188:191], v157 offset:18432
	ds_read_b128 v[192:195], v157 offset:19456
	ds_read_b128 v[196:199], v157 offset:20480
	ds_read_b128 v[200:203], v157 offset:21504
	ds_read_b128 v[204:207], v157 offset:22528
	ds_read_b128 v[208:211], v157 offset:23552
	s_mov_b32 m0, s29
	s_nop 0
	global_load_lds_dwordx4 v152, s[34:35]
	s_add_u32 s84, s34, 0x4000
	s_mov_b32 m0, s62
	s_nop 0
	global_load_lds_dwordx4 v154, s[34:35]
	s_addc_u32 s85, s35, 0
	s_mov_b32 m0, s63
	s_nop 0
	global_load_lds_dwordx4 v152, s[84:85]
	s_nop 0
	s_mov_b32 m0, s64
	s_nop 0
	global_load_lds_dwordx4 v154, s[84:85]
	s_nop 0
	s_mov_b32 m0, s61
	s_nop 0
	global_load_lds_dwordx4 v151, s[36:37]
	s_nop 0
	s_mov_b32 m0, s65
	s_nop 0
	global_load_lds_dwordx4 v153, s[36:37]
	s_waitcnt vmcnt(8)
	s_waitcnt lgkmcnt(0)
	s_setprio 1
	s_barrier
	v_mfma_i32_16x16x64_i8 v[60:63], v[132:135], v[180:183], v[60:63]
	v_mfma_i32_16x16x64_i8 v[60:63], v[136:139], v[184:187], v[60:63]
	v_mfma_i32_16x16x64_i8 v[56:59], v[140:143], v[180:183], v[56:59]
	v_mfma_i32_16x16x64_i8 v[56:59], v[160:163], v[184:187], v[56:59]
	v_mfma_i32_16x16x64_i8 v[48:51], v[140:143], v[188:191], v[48:51]
	v_mfma_i32_16x16x64_i8 v[48:51], v[160:163], v[192:195], v[48:51]
	v_mfma_i32_16x16x64_i8 v[52:55], v[132:135], v[188:191], v[52:55]
	v_mfma_i32_16x16x64_i8 v[52:55], v[136:139], v[192:195], v[52:55]
	v_mfma_i32_16x16x64_i8 v[44:47], v[132:135], v[196:199], v[44:47]
	v_mfma_i32_16x16x64_i8 v[44:47], v[136:139], v[200:203], v[44:47]
	v_mfma_i32_16x16x64_i8 v[40:43], v[140:143], v[196:199], v[40:43]
	v_mfma_i32_16x16x64_i8 v[40:43], v[160:163], v[200:203], v[40:43]
	v_mfma_i32_16x16x64_i8 v[32:35], v[140:143], v[204:207], v[32:35]
	v_mfma_i32_16x16x64_i8 v[32:35], v[160:163], v[208:211], v[32:35]
	v_mfma_i32_16x16x64_i8 v[36:39], v[132:135], v[204:207], v[36:39]
	v_mfma_i32_16x16x64_i8 v[36:39], v[136:139], v[208:211], v[36:39]
	s_setprio 0
	s_setprio 1
	v_mfma_i32_16x16x64_i8 v[28:31], v[164:167], v[180:183], v[28:31]
	v_mfma_i32_16x16x64_i8 v[28:31], v[168:171], v[184:187], v[28:31]
	v_mfma_i32_16x16x64_i8 v[24:27], v[172:175], v[180:183], v[24:27]
	v_mfma_i32_16x16x64_i8 v[24:27], v[176:179], v[184:187], v[24:27]
	v_mfma_i32_16x16x64_i8 v[16:19], v[172:175], v[188:191], v[16:19]
	v_mfma_i32_16x16x64_i8 v[16:19], v[176:179], v[192:195], v[16:19]
	v_mfma_i32_16x16x64_i8 v[20:23], v[164:167], v[188:191], v[20:23]
	v_mfma_i32_16x16x64_i8 v[20:23], v[168:171], v[192:195], v[20:23]
	v_mfma_i32_16x16x64_i8 v[12:15], v[164:167], v[196:199], v[12:15]
	v_mfma_i32_16x16x64_i8 v[12:15], v[168:171], v[200:203], v[12:15]
	v_mfma_i32_16x16x64_i8 v[8:11], v[172:175], v[196:199], v[8:11]
	v_mfma_i32_16x16x64_i8 v[8:11], v[176:179], v[200:203], v[8:11]
	v_mfma_i32_16x16x64_i8 v[0:3], v[172:175], v[204:207], v[0:3]
	v_mfma_i32_16x16x64_i8 v[0:3], v[176:179], v[208:211], v[0:3]
	v_mfma_i32_16x16x64_i8 v[4:7], v[164:167], v[204:207], v[4:7]
	v_mfma_i32_16x16x64_i8 v[4:7], v[168:171], v[208:211], v[4:7]
	s_setprio 0
	s_barrier
	ds_read_b128 v[132:135], v158
	ds_read_b128 v[136:139], v158 offset:1024
	ds_read_b128 v[140:143], v158 offset:2048
	ds_read_b128 v[160:163], v158 offset:3072
	ds_read_b128 v[164:167], v159
	ds_read_b128 v[168:171], v159 offset:1024
	ds_read_b128 v[172:175], v159 offset:2048
	ds_read_b128 v[176:179], v159 offset:3072
	ds_read_b128 v[180:183], v157 offset:32768
	ds_read_b128 v[184:187], v157 offset:33792
	ds_read_b128 v[188:191], v157 offset:34816
	ds_read_b128 v[192:195], v157 offset:35840
	ds_read_b128 v[196:199], v157 offset:36864
	ds_read_b128 v[200:203], v157 offset:37888
	ds_read_b128 v[204:207], v157 offset:38912
	ds_read_b128 v[208:211], v157 offset:39936
	s_add_u32 s36, s36, 0x4000
	s_addc_u32 s37, s37, 0
	s_mov_b32 m0, s66
	s_nop 0
	global_load_lds_dwordx4 v151, s[36:37]
	s_nop 0
	s_mov_b32 m0, s67
	s_nop 0
	global_load_lds_dwordx4 v153, s[36:37]
	s_waitcnt vmcnt(8)
	s_waitcnt lgkmcnt(0)
	s_setprio 1
	s_barrier
	v_mfma_i32_16x16x64_i8 v[124:127], v[132:135], v[180:183], v[124:127]
	v_mfma_i32_16x16x64_i8 v[124:127], v[136:139], v[184:187], v[124:127]
	v_mfma_i32_16x16x64_i8 v[120:123], v[140:143], v[180:183], v[120:123]
	v_mfma_i32_16x16x64_i8 v[120:123], v[160:163], v[184:187], v[120:123]
	v_mfma_i32_16x16x64_i8 v[112:115], v[140:143], v[188:191], v[112:115]
	v_mfma_i32_16x16x64_i8 v[112:115], v[160:163], v[192:195], v[112:115]
	v_mfma_i32_16x16x64_i8 v[116:119], v[132:135], v[188:191], v[116:119]
	v_mfma_i32_16x16x64_i8 v[116:119], v[136:139], v[192:195], v[116:119]
	v_mfma_i32_16x16x64_i8 v[108:111], v[132:135], v[196:199], v[108:111]
	v_mfma_i32_16x16x64_i8 v[108:111], v[136:139], v[200:203], v[108:111]
	v_mfma_i32_16x16x64_i8 v[104:107], v[140:143], v[196:199], v[104:107]
	v_mfma_i32_16x16x64_i8 v[104:107], v[160:163], v[200:203], v[104:107]
	v_mfma_i32_16x16x64_i8 v[96:99], v[140:143], v[204:207], v[96:99]
	v_mfma_i32_16x16x64_i8 v[96:99], v[160:163], v[208:211], v[96:99]
	v_mfma_i32_16x16x64_i8 v[100:103], v[132:135], v[204:207], v[100:103]
	v_mfma_i32_16x16x64_i8 v[100:103], v[136:139], v[208:211], v[100:103]
	s_setprio 0
	s_setprio 1
	v_mfma_i32_16x16x64_i8 v[92:95], v[164:167], v[180:183], v[92:95]
	v_mfma_i32_16x16x64_i8 v[92:95], v[168:171], v[184:187], v[92:95]
	v_mfma_i32_16x16x64_i8 v[88:91], v[172:175], v[180:183], v[88:91]
	v_mfma_i32_16x16x64_i8 v[88:91], v[176:179], v[184:187], v[88:91]
	v_mfma_i32_16x16x64_i8 v[80:83], v[172:175], v[188:191], v[80:83]
	v_mfma_i32_16x16x64_i8 v[80:83], v[176:179], v[192:195], v[80:83]
	v_mfma_i32_16x16x64_i8 v[84:87], v[164:167], v[188:191], v[84:87]
	v_mfma_i32_16x16x64_i8 v[84:87], v[168:171], v[192:195], v[84:87]
	v_mfma_i32_16x16x64_i8 v[76:79], v[164:167], v[196:199], v[76:79]
	v_mfma_i32_16x16x64_i8 v[76:79], v[168:171], v[200:203], v[76:79]
	v_mfma_i32_16x16x64_i8 v[72:75], v[172:175], v[196:199], v[72:75]
	v_mfma_i32_16x16x64_i8 v[72:75], v[176:179], v[200:203], v[72:75]
	v_mfma_i32_16x16x64_i8 v[64:67], v[172:175], v[204:207], v[64:67]
	v_mfma_i32_16x16x64_i8 v[64:67], v[176:179], v[208:211], v[64:67]
	v_mfma_i32_16x16x64_i8 v[68:71], v[164:167], v[204:207], v[68:71]
	v_mfma_i32_16x16x64_i8 v[68:71], v[168:171], v[208:211], v[68:71]
	s_setprio 0
	s_barrier
	ds_read_b128 v[180:183], v157 offset:49152
	ds_read_b128 v[184:187], v157 offset:50176
	ds_read_b128 v[188:191], v157 offset:51200
	ds_read_b128 v[192:195], v157 offset:52224
	ds_read_b128 v[196:199], v157 offset:53248
	ds_read_b128 v[200:203], v157 offset:54272
	ds_read_b128 v[204:207], v157 offset:55296
	ds_read_b128 v[208:211], v157 offset:56320
	s_add_u32 s36, s34, 0x8000
	s_addc_u32 s37, s35, 0
	s_mov_b32 m0, s68
	s_nop 0
	global_load_lds_dwordx4 v152, s[36:37]
	s_add_u32 s34, s34, 0xc000
	s_mov_b32 m0, s69
	s_nop 0
	global_load_lds_dwordx4 v154, s[36:37]
	s_addc_u32 s35, s35, 0
	s_mov_b32 m0, s72
	s_nop 0
	global_load_lds_dwordx4 v152, s[34:35]
	s_nop 0
	s_mov_b32 m0, s73
	s_nop 0
	global_load_lds_dwordx4 v154, s[34:35]
	s_nop 0
	s_mov_b32 m0, s70
	s_nop 0
	global_load_lds_dwordx4 v151, s[30:31]
	s_nop 0
	s_mov_b32 m0, s71
	s_nop 0
	global_load_lds_dwordx4 v153, s[30:31]
	s_waitcnt vmcnt(8)
	s_waitcnt lgkmcnt(0)
	s_setprio 1
	s_barrier
	v_mfma_i32_16x16x64_i8 v[60:63], v[132:135], v[180:183], v[60:63]
	v_mfma_i32_16x16x64_i8 v[60:63], v[136:139], v[184:187], v[60:63]
	v_mfma_i32_16x16x64_i8 v[56:59], v[140:143], v[180:183], v[56:59]
	v_mfma_i32_16x16x64_i8 v[56:59], v[160:163], v[184:187], v[56:59]
	v_mfma_i32_16x16x64_i8 v[48:51], v[140:143], v[188:191], v[48:51]
	v_mfma_i32_16x16x64_i8 v[48:51], v[160:163], v[192:195], v[48:51]
	v_mfma_i32_16x16x64_i8 v[52:55], v[132:135], v[188:191], v[52:55]
	v_mfma_i32_16x16x64_i8 v[52:55], v[136:139], v[192:195], v[52:55]
	v_mfma_i32_16x16x64_i8 v[44:47], v[132:135], v[196:199], v[44:47]
	v_mfma_i32_16x16x64_i8 v[44:47], v[136:139], v[200:203], v[44:47]
	v_mfma_i32_16x16x64_i8 v[40:43], v[140:143], v[196:199], v[40:43]
	v_mfma_i32_16x16x64_i8 v[40:43], v[160:163], v[200:203], v[40:43]
	v_mfma_i32_16x16x64_i8 v[32:35], v[140:143], v[204:207], v[32:35]
	v_mfma_i32_16x16x64_i8 v[32:35], v[160:163], v[208:211], v[32:35]
	v_mfma_i32_16x16x64_i8 v[36:39], v[132:135], v[204:207], v[36:39]
	v_mfma_i32_16x16x64_i8 v[36:39], v[136:139], v[208:211], v[36:39]
	s_setprio 0
	s_setprio 1
	v_mfma_i32_16x16x64_i8 v[28:31], v[164:167], v[180:183], v[28:31]
	v_mfma_i32_16x16x64_i8 v[28:31], v[168:171], v[184:187], v[28:31]
	v_mfma_i32_16x16x64_i8 v[24:27], v[172:175], v[180:183], v[24:27]
	v_mfma_i32_16x16x64_i8 v[24:27], v[176:179], v[184:187], v[24:27]
	v_mfma_i32_16x16x64_i8 v[16:19], v[172:175], v[188:191], v[16:19]
	v_mfma_i32_16x16x64_i8 v[16:19], v[176:179], v[192:195], v[16:19]
	v_mfma_i32_16x16x64_i8 v[20:23], v[164:167], v[188:191], v[20:23]
	v_mfma_i32_16x16x64_i8 v[20:23], v[168:171], v[192:195], v[20:23]
	v_mfma_i32_16x16x64_i8 v[12:15], v[164:167], v[196:199], v[12:15]
	v_mfma_i32_16x16x64_i8 v[12:15], v[168:171], v[200:203], v[12:15]
	v_mfma_i32_16x16x64_i8 v[8:11], v[172:175], v[196:199], v[8:11]
	v_mfma_i32_16x16x64_i8 v[8:11], v[176:179], v[200:203], v[8:11]
	v_mfma_i32_16x16x64_i8 v[0:3], v[172:175], v[204:207], v[0:3]
	v_mfma_i32_16x16x64_i8 v[0:3], v[176:179], v[208:211], v[0:3]
	v_mfma_i32_16x16x64_i8 v[4:7], v[164:167], v[204:207], v[4:7]
	v_mfma_i32_16x16x64_i8 v[4:7], v[168:171], v[208:211], v[4:7]
	s_setprio 0
	s_barrier
	s_add_i32 s82, s82, 2
	s_add_u32 s78, s78, 0x10000
	s_addc_u32 s79, s79, 0
	s_add_u32 s80, s80, 0x10000
	s_addc_u32 s81, s81, 0
	s_cmp_gt_u32 s82, 29
	s_cbranch_scc0 .LBB0_129
	s_and_b64 vcc, exec, s[14:15]
	s_cbranch_vccz .LBB0_132
	s_barrier
